# v009 + P7/P12 SwiGLU epilogue VALU stream rewritten by hand: rstd folded as out=(g*u)*rcp(fma(2^(c1*g),q,q)) with q=mean(x^2)+eps (same f32 math re-associated), 45 instead of 59 VALU per row group, on
# speedup vs baseline: 1.0121x; 1.0121x over previous
; __device__ __forceinline__ unsigned cvt_pk_bf16(float lo, float hi) { const cvt_f32x2_t v = {lo, hi}; const cvt_bf16x2_t b = __builtin_convertvector(v, cvt_bf16x2_t); return __builtin_bit_cast(unsigned, b); }
; __device__ __forceinline__ float rstd_from_slots(const float* slots, int row, int fq) {
;     const f32x4 s4 = *(const f32x4*)(slots + (size_t)row * 16 + 4 * fq);
;     float s = (s4[0] + s4[1]) + (s4[2] + s4[3]);
;     s += __shfl_xor(s, 16); s += __shfl_xor(s, 32);
;     return __builtin_amdgcn_rsqf(s * (1.0f / 1024.0f) + RMS_EPS_F);
; __device__ __forceinline__ float silu_mul(float g, float u) { return g * u * __builtin_amdgcn_rcpf(1.0f + __builtin_amdgcn_exp2f(g * -1.4426950408889634f)); }
;     __device__ __forceinline__ void operator()(const f32x4 (&acc)[2][2][4][2], const Unit& u, int wr, int wc, int fr, int fq) const {
;         const int row0 = u.pm * BM + wr * 64 + fr; const int col0 = u.pn * HALF + wc * 32 + 8 * fq;
; #pragma unroll
;         for (int ai = 0; ai < 2; ++ai)
; #pragma unroll
;             for (int m = 0; m < 4; ++m) { const int row = row0 + ai * HALF + m * 16;
;                 const float sc = rstd_from_slots(slots, row, fq);
;                 const f32x4 g0 = acc[ai][0][m][0] * sc, g1 = acc[ai][0][m][1] * sc, u0 = acc[ai][1][m][0] * sc, u1 = acc[ai][1][m][1] * sc;
;                 u32x4 w; w.x = cvt_pk_bf16(silu_mul(g0[0], u0[0]), silu_mul(g0[1], u0[1])); w.y = cvt_pk_bf16(silu_mul(g0[2], u0[2]), silu_mul(g0[3], u0[3]));
;                 w.z = cvt_pk_bf16(silu_mul(g1[0], u1[0]), silu_mul(g1[1], u1[1])); w.w = cvt_pk_bf16(silu_mul(g1[2], u1[2]), silu_mul(g1[3], u1[3]));
;                 __builtin_nontemporal_store(w, (u32x4*)(O + (size_t)row * ldc + col0)); }
.LBB0_675:
	v_xor_b32_e32 v216, 16, v161
	v_xor_b32_e32 v217, 32, v161
	v_lshlrev_b32_e32 v216, 2, v216
	v_lshlrev_b32_e32 v217, 2, v217
	s_waitcnt vmcnt(0)
	v_add_f32_e32 v172, v172, v173
	v_add_f32_e32 v173, v175, v174
	v_add_f32_e32 v176, v176, v177
	v_add_f32_e32 v177, v179, v178
	v_add_f32_e32 v180, v180, v181
	v_add_f32_e32 v181, v183, v182
	v_add_f32_e32 v184, v184, v185
	v_add_f32_e32 v185, v187, v186
	v_add_f32_e32 v188, v188, v189
	v_add_f32_e32 v189, v191, v190
	v_add_f32_e32 v192, v192, v193
	v_add_f32_e32 v193, v195, v194
	v_add_f32_e32 v196, v196, v197
	v_add_f32_e32 v197, v199, v198
	v_add_f32_e32 v200, v200, v201
	v_add_f32_e32 v201, v203, v202
	v_add_f32_e32 v172, v172, v173
	v_add_f32_e32 v176, v176, v177
	v_add_f32_e32 v180, v180, v181
	v_add_f32_e32 v184, v184, v185
	v_add_f32_e32 v188, v188, v189
	v_add_f32_e32 v192, v192, v193
	v_add_f32_e32 v196, v196, v197
	v_add_f32_e32 v200, v200, v201
	ds_bpermute_b32 v173, v216, v172
	ds_bpermute_b32 v177, v216, v176
	ds_bpermute_b32 v181, v216, v180
	ds_bpermute_b32 v185, v216, v184
	ds_bpermute_b32 v189, v216, v188
	ds_bpermute_b32 v193, v216, v192
	ds_bpermute_b32 v197, v216, v196
	ds_bpermute_b32 v201, v216, v200
	s_waitcnt lgkmcnt(0)
	v_add_f32_e32 v172, v172, v173
	v_add_f32_e32 v176, v176, v177
	v_add_f32_e32 v180, v180, v181
	v_add_f32_e32 v184, v184, v185
	v_add_f32_e32 v188, v188, v189
	v_add_f32_e32 v192, v192, v193
	v_add_f32_e32 v196, v196, v197
	v_add_f32_e32 v200, v200, v201
	ds_bpermute_b32 v173, v217, v172
	ds_bpermute_b32 v177, v217, v176
	ds_bpermute_b32 v181, v217, v180
	ds_bpermute_b32 v185, v217, v184
	ds_bpermute_b32 v189, v217, v188
	ds_bpermute_b32 v193, v217, v192
	ds_bpermute_b32 v197, v217, v196
	ds_bpermute_b32 v201, v217, v200
	s_waitcnt lgkmcnt(0)
	v_add_f32_e32 v172, v172, v173
	v_add_f32_e32 v176, v176, v177
	v_add_f32_e32 v180, v180, v181
	v_add_f32_e32 v184, v184, v185
	v_add_f32_e32 v188, v188, v189
	v_add_f32_e32 v192, v192, v193
	v_add_f32_e32 v196, v196, v197
	v_add_f32_e32 v200, v200, v201
	v_fmamk_f32 v173, v172, 0x3a800000, v162
	v_fmamk_f32 v177, v176, 0x3a800000, v162
	v_fmamk_f32 v181, v180, 0x3a800000, v162
	v_fmamk_f32 v185, v184, 0x3a800000, v162
	v_fmamk_f32 v189, v188, 0x3a800000, v162
	v_fmamk_f32 v193, v192, 0x3a800000, v162
	v_fmamk_f32 v197, v196, 0x3a800000, v162
	v_fmamk_f32 v201, v200, 0x3a800000, v162
	v_rsq_f32_e32 v172, v173
	v_rsq_f32_e32 v176, v177
	v_rsq_f32_e32 v180, v181
	v_rsq_f32_e32 v184, v185
	v_rsq_f32_e32 v188, v189
	v_rsq_f32_e32 v192, v193
	v_rsq_f32_e32 v196, v197
	v_rsq_f32_e32 v200, v201
	v_mul_f32_e32 v172, 0xbfb8aa3b, v172
	v_mul_f32_e32 v176, 0xbfb8aa3b, v176
	v_mul_f32_e32 v180, 0xbfb8aa3b, v180
	v_mul_f32_e32 v184, 0xbfb8aa3b, v184
	v_mul_f32_e32 v188, 0xbfb8aa3b, v188
	v_mul_f32_e32 v192, 0xbfb8aa3b, v192
	v_mul_f32_e32 v196, 0xbfb8aa3b, v196
	v_mul_f32_e32 v200, 0xbfb8aa3b, v200
	v_lshl_add_u32 v150, s0, 8, v152
	v_lshl_or_b32 v148, s1, 7, v157
	v_mov_b64_e32 v[146:147], s[10:11]
	v_ashrrev_i32_e32 v149, 31, v148
	v_lshlrev_b64 v[148:149], 1, v[148:149]
	s_andn2_b64 vcc, exec, s[2:3]
	v_mad_i64_i32 v[164:165], s[0:1], v150, s56, v[146:147]
	v_lshl_add_u64 v[164:165], v[164:165], 0, v[148:149]
	s_mov_b64 s[0:1], -1
	s_mov_b32 s98, 0x16000
	s_mov_b32 s99, 0
	v_pk_mul_f32 v[112:113], v[120:121], v[112:113]
	v_pk_mul_f32 v[114:115], v[122:123], v[114:115]
	v_pk_mul_f32 v[116:117], v[124:125], v[116:117]
	v_pk_mul_f32 v[118:119], v[126:127], v[118:119]
	v_mul_f32_e32 v120, v172, v120
	v_mul_f32_e32 v121, v172, v121
	v_mul_f32_e32 v122, v172, v122
	v_mul_f32_e32 v123, v172, v123
	v_mul_f32_e32 v124, v172, v124
	v_mul_f32_e32 v125, v172, v125
	v_mul_f32_e32 v126, v172, v126
	v_mul_f32_e32 v127, v172, v127
	v_exp_f32_e32 v120, v120
	v_exp_f32_e32 v121, v121
	v_exp_f32_e32 v122, v122
	v_exp_f32_e32 v123, v123
	v_exp_f32_e32 v124, v124
	v_exp_f32_e32 v125, v125
	v_exp_f32_e32 v126, v126
	v_exp_f32_e32 v127, v127
	v_fma_f32 v120, v120, v173, v173
	v_fma_f32 v121, v121, v173, v173
	v_fma_f32 v122, v122, v173, v173
	v_fma_f32 v123, v123, v173, v173
	v_fma_f32 v124, v124, v173, v173
	v_fma_f32 v125, v125, v173, v173
	v_fma_f32 v126, v126, v173, v173
	v_fma_f32 v127, v127, v173, v173
	v_rcp_f32_e32 v120, v120
	v_rcp_f32_e32 v121, v121
	v_rcp_f32_e32 v122, v122
	v_rcp_f32_e32 v123, v123
	v_rcp_f32_e32 v124, v124
	v_rcp_f32_e32 v125, v125
	v_rcp_f32_e32 v126, v126
	v_rcp_f32_e32 v127, v127
	v_pk_mul_f32 v[112:113], v[112:113], v[120:121]
	v_pk_mul_f32 v[114:115], v[114:115], v[122:123]
	v_pk_mul_f32 v[116:117], v[116:117], v[124:125]
	v_pk_mul_f32 v[118:119], v[118:119], v[126:127]
	v_cvt_pk_bf16_f32 v120, v116, v117
	v_cvt_pk_bf16_f32 v121, v118, v119
	v_cvt_pk_bf16_f32 v122, v112, v113
	v_cvt_pk_bf16_f32 v123, v114, v115
	global_store_dwordx4 v[164:165], v[120:123], off nt
	v_lshl_add_u64 v[166:167], v[164:165], 0, s[98:99]
	v_pk_mul_f32 v[96:97], v[104:105], v[96:97]
	v_pk_mul_f32 v[98:99], v[106:107], v[98:99]
	v_pk_mul_f32 v[100:101], v[108:109], v[100:101]
	v_pk_mul_f32 v[102:103], v[110:111], v[102:103]
	v_mul_f32_e32 v104, v176, v104
	v_mul_f32_e32 v105, v176, v105
	v_mul_f32_e32 v106, v176, v106
	v_mul_f32_e32 v107, v176, v107
	v_mul_f32_e32 v108, v176, v108
	v_mul_f32_e32 v109, v176, v109
	v_mul_f32_e32 v110, v176, v110
	v_mul_f32_e32 v111, v176, v111
	v_exp_f32_e32 v104, v104
	v_exp_f32_e32 v105, v105
	v_exp_f32_e32 v106, v106
	v_exp_f32_e32 v107, v107
	v_exp_f32_e32 v108, v108
	v_exp_f32_e32 v109, v109
	v_exp_f32_e32 v110, v110
	v_exp_f32_e32 v111, v111
	v_fma_f32 v104, v104, v177, v177
	v_fma_f32 v105, v105, v177, v177
	v_fma_f32 v106, v106, v177, v177
	v_fma_f32 v107, v107, v177, v177
; __device__ __forceinline__ unsigned cvt_pk_bf16(float lo, float hi) { const cvt_f32x2_t v = {lo, hi}; const cvt_bf16x2_t b = __builtin_convertvector(v, cvt_bf16x2_t); return __builtin_bit_cast(unsigned, b); }
; __device__ __forceinline__ float silu_mul(float g, float u) { return g * u * __builtin_amdgcn_rcpf(1.0f + __builtin_amdgcn_exp2f(g * -1.4426950408889634f)); }
;     __device__ __forceinline__ void operator()(const f32x4 (&acc)[2][2][4][2], const Unit& u, int wr, int wc, int fr, int fq) const {
;     ...
; #pragma unroll
;         for (int ai = 0; ai < 2; ++ai)
; #pragma unroll
;             for (int m = 0; m < 4; ++m) { const int row = row0 + ai * HALF + m * 16;
;                 const float sc = rstd_from_slots(slots, row, fq);
;                 const f32x4 g0 = acc[ai][0][m][0] * sc, g1 = acc[ai][0][m][1] * sc, u0 = acc[ai][1][m][0] * sc, u1 = acc[ai][1][m][1] * sc;
;                 u32x4 w; w.x = cvt_pk_bf16(silu_mul(g0[0], u0[0]), silu_mul(g0[1], u0[1])); w.y = cvt_pk_bf16(silu_mul(g0[2], u0[2]), silu_mul(g0[3], u0[3]));
;                 w.z = cvt_pk_bf16(silu_mul(g1[0], u1[0]), silu_mul(g1[1], u1[1])); w.w = cvt_pk_bf16(silu_mul(g1[2], u1[2]), silu_mul(g1[3], u1[3]));
;                 __builtin_nontemporal_store(w, (u32x4*)(O + (size_t)row * ldc + col0)); }
	v_fma_f32 v108, v108, v177, v177
	v_fma_f32 v109, v109, v177, v177
	v_fma_f32 v110, v110, v177, v177
	v_fma_f32 v111, v111, v177, v177
	v_rcp_f32_e32 v104, v104
	v_rcp_f32_e32 v105, v105
	v_rcp_f32_e32 v106, v106
	v_rcp_f32_e32 v107, v107
	v_rcp_f32_e32 v108, v108
	v_rcp_f32_e32 v109, v109
	v_rcp_f32_e32 v110, v110
	v_rcp_f32_e32 v111, v111
	v_pk_mul_f32 v[96:97], v[96:97], v[104:105]
	v_pk_mul_f32 v[98:99], v[98:99], v[106:107]
	v_pk_mul_f32 v[100:101], v[100:101], v[108:109]
	v_pk_mul_f32 v[102:103], v[102:103], v[110:111]
	v_cvt_pk_bf16_f32 v104, v100, v101
	v_cvt_pk_bf16_f32 v105, v102, v103
	v_cvt_pk_bf16_f32 v106, v96, v97
	v_cvt_pk_bf16_f32 v107, v98, v99
	global_store_dwordx4 v[166:167], v[104:107], off nt
	v_lshl_add_u64 v[164:165], v[166:167], 0, s[98:99]
	v_pk_mul_f32 v[80:81], v[88:89], v[80:81]
	v_pk_mul_f32 v[82:83], v[90:91], v[82:83]
	v_pk_mul_f32 v[84:85], v[92:93], v[84:85]
	v_pk_mul_f32 v[86:87], v[94:95], v[86:87]
	v_mul_f32_e32 v88, v180, v88
	v_mul_f32_e32 v89, v180, v89
	v_mul_f32_e32 v90, v180, v90
	v_mul_f32_e32 v91, v180, v91
	v_mul_f32_e32 v92, v180, v92
	v_mul_f32_e32 v93, v180, v93
	v_mul_f32_e32 v94, v180, v94
	v_mul_f32_e32 v95, v180, v95
	v_exp_f32_e32 v88, v88
	v_exp_f32_e32 v89, v89
	v_exp_f32_e32 v90, v90
	v_exp_f32_e32 v91, v91
	v_exp_f32_e32 v92, v92
	v_exp_f32_e32 v93, v93
	v_exp_f32_e32 v94, v94
	v_exp_f32_e32 v95, v95
	v_fma_f32 v88, v88, v181, v181
	v_fma_f32 v89, v89, v181, v181
	v_fma_f32 v90, v90, v181, v181
	v_fma_f32 v91, v91, v181, v181
	v_fma_f32 v92, v92, v181, v181
	v_fma_f32 v93, v93, v181, v181
	v_fma_f32 v94, v94, v181, v181
	v_fma_f32 v95, v95, v181, v181
	v_rcp_f32_e32 v88, v88
	v_rcp_f32_e32 v89, v89
	v_rcp_f32_e32 v90, v90
	v_rcp_f32_e32 v91, v91
	v_rcp_f32_e32 v92, v92
	v_rcp_f32_e32 v93, v93
	v_rcp_f32_e32 v94, v94
	v_rcp_f32_e32 v95, v95
	v_pk_mul_f32 v[80:81], v[80:81], v[88:89]
	v_pk_mul_f32 v[82:83], v[82:83], v[90:91]
	v_pk_mul_f32 v[84:85], v[84:85], v[92:93]
	v_pk_mul_f32 v[86:87], v[86:87], v[94:95]
	v_cvt_pk_bf16_f32 v88, v84, v85
	v_cvt_pk_bf16_f32 v89, v86, v87
	v_cvt_pk_bf16_f32 v90, v80, v81
	v_cvt_pk_bf16_f32 v91, v82, v83
	global_store_dwordx4 v[164:165], v[88:91], off nt
	v_lshl_add_u64 v[166:167], v[164:165], 0, s[98:99]
	v_pk_mul_f32 v[64:65], v[72:73], v[64:65]
	v_pk_mul_f32 v[66:67], v[74:75], v[66:67]
	v_pk_mul_f32 v[68:69], v[76:77], v[68:69]
	v_pk_mul_f32 v[70:71], v[78:79], v[70:71]
	v_mul_f32_e32 v72, v184, v72
	v_mul_f32_e32 v73, v184, v73
	v_mul_f32_e32 v74, v184, v74
	v_mul_f32_e32 v75, v184, v75
	v_mul_f32_e32 v76, v184, v76
	v_mul_f32_e32 v77, v184, v77
	v_mul_f32_e32 v78, v184, v78
	v_mul_f32_e32 v79, v184, v79
	v_exp_f32_e32 v72, v72
	v_exp_f32_e32 v73, v73
	v_exp_f32_e32 v74, v74
	v_exp_f32_e32 v75, v75
	v_exp_f32_e32 v76, v76
	v_exp_f32_e32 v77, v77
	v_exp_f32_e32 v78, v78
	v_exp_f32_e32 v79, v79
	v_fma_f32 v72, v72, v185, v185
	v_fma_f32 v73, v73, v185, v185
	v_fma_f32 v74, v74, v185, v185
	v_fma_f32 v75, v75, v185, v185
	v_fma_f32 v76, v76, v185, v185
	v_fma_f32 v77, v77, v185, v185
	v_fma_f32 v78, v78, v185, v185
	v_fma_f32 v79, v79, v185, v185
	v_rcp_f32_e32 v72, v72
	v_rcp_f32_e32 v73, v73
	v_rcp_f32_e32 v74, v74
	v_rcp_f32_e32 v75, v75
	v_rcp_f32_e32 v76, v76
	v_rcp_f32_e32 v77, v77
	v_rcp_f32_e32 v78, v78
	v_rcp_f32_e32 v79, v79
	v_pk_mul_f32 v[64:65], v[64:65], v[72:73]
	v_pk_mul_f32 v[66:67], v[66:67], v[74:75]
	v_pk_mul_f32 v[68:69], v[68:69], v[76:77]
	v_pk_mul_f32 v[70:71], v[70:71], v[78:79]
	v_cvt_pk_bf16_f32 v72, v68, v69
	v_cvt_pk_bf16_f32 v73, v70, v71
	v_cvt_pk_bf16_f32 v74, v64, v65
	v_cvt_pk_bf16_f32 v75, v66, v67
	global_store_dwordx4 v[166:167], v[72:75], off nt
	s_mov_b32 s98, 0x6e000
	v_lshl_add_u64 v[164:165], v[166:167], 0, s[98:99]
	s_mov_b32 s98, 0x16000
	v_pk_mul_f32 v[48:49], v[56:57], v[48:49]
	v_pk_mul_f32 v[50:51], v[58:59], v[50:51]
	v_pk_mul_f32 v[52:53], v[60:61], v[52:53]
	v_pk_mul_f32 v[54:55], v[62:63], v[54:55]
	v_mul_f32_e32 v56, v188, v56
	v_mul_f32_e32 v57, v188, v57
	v_mul_f32_e32 v58, v188, v58
	v_mul_f32_e32 v59, v188, v59
	v_mul_f32_e32 v60, v188, v60
	v_mul_f32_e32 v61, v188, v61
	v_mul_f32_e32 v62, v188, v62
	v_mul_f32_e32 v63, v188, v63
	v_exp_f32_e32 v56, v56
	v_exp_f32_e32 v57, v57
	v_exp_f32_e32 v58, v58
	v_exp_f32_e32 v59, v59
	v_exp_f32_e32 v60, v60
	v_exp_f32_e32 v61, v61
	v_exp_f32_e32 v62, v62
	v_exp_f32_e32 v63, v63
	v_fma_f32 v56, v56, v189, v189
	v_fma_f32 v57, v57, v189, v189
	v_fma_f32 v58, v58, v189, v189
	v_fma_f32 v59, v59, v189, v189
	v_fma_f32 v60, v60, v189, v189
	v_fma_f32 v61, v61, v189, v189
	v_fma_f32 v62, v62, v189, v189
	v_fma_f32 v63, v63, v189, v189
	v_rcp_f32_e32 v56, v56
	v_rcp_f32_e32 v57, v57
	v_rcp_f32_e32 v58, v58
	v_rcp_f32_e32 v59, v59
	v_rcp_f32_e32 v60, v60
	v_rcp_f32_e32 v61, v61
	v_rcp_f32_e32 v62, v62
	v_rcp_f32_e32 v63, v63
; __device__ __forceinline__ unsigned cvt_pk_bf16(float lo, float hi) { const cvt_f32x2_t v = {lo, hi}; const cvt_bf16x2_t b = __builtin_convertvector(v, cvt_bf16x2_t); return __builtin_bit_cast(unsigned, b); }
; __device__ __forceinline__ float silu_mul(float g, float u) { return g * u * __builtin_amdgcn_rcpf(1.0f + __builtin_amdgcn_exp2f(g * -1.4426950408889634f)); }
; #define PG8_BAR __builtin_amdgcn_s_barrier()
;     __device__ __forceinline__ void operator()(const f32x4 (&acc)[2][2][4][2], const Unit& u, int wr, int wc, int fr, int fq) const {
;     ...
; #pragma unroll
;         for (int ai = 0; ai < 2; ++ai)
; #pragma unroll
;             for (int m = 0; m < 4; ++m) { const int row = row0 + ai * HALF + m * 16;
;                 const float sc = rstd_from_slots(slots, row, fq);
;                 const f32x4 g0 = acc[ai][0][m][0] * sc, g1 = acc[ai][0][m][1] * sc, u0 = acc[ai][1][m][0] * sc, u1 = acc[ai][1][m][1] * sc;
;                 u32x4 w; w.x = cvt_pk_bf16(silu_mul(g0[0], u0[0]), silu_mul(g0[1], u0[1])); w.y = cvt_pk_bf16(silu_mul(g0[2], u0[2]), silu_mul(g0[3], u0[3]));
;                 w.z = cvt_pk_bf16(silu_mul(g1[0], u1[0]), silu_mul(g1[1], u1[1])); w.w = cvt_pk_bf16(silu_mul(g1[2], u1[2]), silu_mul(g1[3], u1[3]));
;                 __builtin_nontemporal_store(w, (u32x4*)(O + (size_t)row * ldc + col0)); }
; template <class Epi, class Sched, bool ALIGN_EPI = false, bool SP2 = false>
; __device__ __forceinline__ void gemm_phase(PG8_LAS unsigned char* lds, const Gemm g, const Sched& S, const Epi& E) {
;     ...
;         if constexpr (!Epi::AFTER_DRAIN) { E(acc, cur, wr, wc, fr, fq); S.done(cur); }
;         if (!has_next) break;
; #pragma unroll
;         for (int a = 0; a < 2; ++a)
; #pragma unroll
;             for (int b = 0; b < 2; ++b)
; #pragma unroll
;                 for (int m = 0; m < 4; ++m)
; #pragma unroll
;                     for (int n = 0; n < 2; ++n) acc[a][b][m][n] = (f32x4){0.f, 0.f, 0.f, 0.f};
;         cur = nxt; cA = nA; cB = nB; ++ui;
;         if constexpr (ALIGN_EPI) { if (wr == 1) PG8_BAR; }
	v_pk_mul_f32 v[48:49], v[48:49], v[56:57]
	v_pk_mul_f32 v[50:51], v[50:51], v[58:59]
	v_pk_mul_f32 v[52:53], v[52:53], v[60:61]
	v_pk_mul_f32 v[54:55], v[54:55], v[62:63]
	v_cvt_pk_bf16_f32 v56, v52, v53
	v_cvt_pk_bf16_f32 v57, v54, v55
	v_cvt_pk_bf16_f32 v58, v48, v49
	v_cvt_pk_bf16_f32 v59, v50, v51
	global_store_dwordx4 v[164:165], v[56:59], off nt
	v_lshl_add_u64 v[166:167], v[164:165], 0, s[98:99]
	v_pk_mul_f32 v[32:33], v[40:41], v[32:33]
	v_pk_mul_f32 v[34:35], v[42:43], v[34:35]
	v_pk_mul_f32 v[36:37], v[44:45], v[36:37]
	v_pk_mul_f32 v[38:39], v[46:47], v[38:39]
	v_mul_f32_e32 v40, v192, v40
	v_mul_f32_e32 v41, v192, v41
	v_mul_f32_e32 v42, v192, v42
	v_mul_f32_e32 v43, v192, v43
	v_mul_f32_e32 v44, v192, v44
	v_mul_f32_e32 v45, v192, v45
	v_mul_f32_e32 v46, v192, v46
	v_mul_f32_e32 v47, v192, v47
	v_exp_f32_e32 v40, v40
	v_exp_f32_e32 v41, v41
	v_exp_f32_e32 v42, v42
	v_exp_f32_e32 v43, v43
	v_exp_f32_e32 v44, v44
	v_exp_f32_e32 v45, v45
	v_exp_f32_e32 v46, v46
	v_exp_f32_e32 v47, v47
	v_fma_f32 v40, v40, v193, v193
	v_fma_f32 v41, v41, v193, v193
	v_fma_f32 v42, v42, v193, v193
	v_fma_f32 v43, v43, v193, v193
	v_fma_f32 v44, v44, v193, v193
	v_fma_f32 v45, v45, v193, v193
	v_fma_f32 v46, v46, v193, v193
	v_fma_f32 v47, v47, v193, v193
	v_rcp_f32_e32 v40, v40
	v_rcp_f32_e32 v41, v41
	v_rcp_f32_e32 v42, v42
	v_rcp_f32_e32 v43, v43
	v_rcp_f32_e32 v44, v44
	v_rcp_f32_e32 v45, v45
	v_rcp_f32_e32 v46, v46
	v_rcp_f32_e32 v47, v47
	v_pk_mul_f32 v[32:33], v[32:33], v[40:41]
	v_pk_mul_f32 v[34:35], v[34:35], v[42:43]
	v_pk_mul_f32 v[36:37], v[36:37], v[44:45]
	v_pk_mul_f32 v[38:39], v[38:39], v[46:47]
	v_cvt_pk_bf16_f32 v40, v36, v37
	v_cvt_pk_bf16_f32 v41, v38, v39
	v_cvt_pk_bf16_f32 v42, v32, v33
	v_cvt_pk_bf16_f32 v43, v34, v35
	global_store_dwordx4 v[166:167], v[40:43], off nt
	v_lshl_add_u64 v[164:165], v[166:167], 0, s[98:99]
	v_pk_mul_f32 v[16:17], v[24:25], v[16:17]
	v_pk_mul_f32 v[18:19], v[26:27], v[18:19]
	v_pk_mul_f32 v[20:21], v[28:29], v[20:21]
	v_pk_mul_f32 v[22:23], v[30:31], v[22:23]
	v_mul_f32_e32 v24, v196, v24
	v_mul_f32_e32 v25, v196, v25
	v_mul_f32_e32 v26, v196, v26
	v_mul_f32_e32 v27, v196, v27
	v_mul_f32_e32 v28, v196, v28
	v_mul_f32_e32 v29, v196, v29
	v_mul_f32_e32 v30, v196, v30
	v_mul_f32_e32 v31, v196, v31
	v_exp_f32_e32 v24, v24
	v_exp_f32_e32 v25, v25
	v_exp_f32_e32 v26, v26
	v_exp_f32_e32 v27, v27
	v_exp_f32_e32 v28, v28
	v_exp_f32_e32 v29, v29
	v_exp_f32_e32 v30, v30
	v_exp_f32_e32 v31, v31
	v_fma_f32 v24, v24, v197, v197
	v_fma_f32 v25, v25, v197, v197
	v_fma_f32 v26, v26, v197, v197
	v_fma_f32 v27, v27, v197, v197
	v_fma_f32 v28, v28, v197, v197
	v_fma_f32 v29, v29, v197, v197
	v_fma_f32 v30, v30, v197, v197
	v_fma_f32 v31, v31, v197, v197
	v_rcp_f32_e32 v24, v24
	v_rcp_f32_e32 v25, v25
	v_rcp_f32_e32 v26, v26
	v_rcp_f32_e32 v27, v27
	v_rcp_f32_e32 v28, v28
	v_rcp_f32_e32 v29, v29
	v_rcp_f32_e32 v30, v30
	v_rcp_f32_e32 v31, v31
	v_pk_mul_f32 v[16:17], v[16:17], v[24:25]
	v_pk_mul_f32 v[18:19], v[18:19], v[26:27]
	v_pk_mul_f32 v[20:21], v[20:21], v[28:29]
	v_pk_mul_f32 v[22:23], v[22:23], v[30:31]
	v_cvt_pk_bf16_f32 v24, v20, v21
	v_cvt_pk_bf16_f32 v25, v22, v23
	v_cvt_pk_bf16_f32 v26, v16, v17
	v_cvt_pk_bf16_f32 v27, v18, v19
	global_store_dwordx4 v[164:165], v[24:27], off nt
	v_lshl_add_u64 v[166:167], v[164:165], 0, s[98:99]
	v_pk_mul_f32 v[0:1], v[8:9], v[0:1]
	v_pk_mul_f32 v[2:3], v[10:11], v[2:3]
	v_pk_mul_f32 v[4:5], v[12:13], v[4:5]
	v_pk_mul_f32 v[6:7], v[14:15], v[6:7]
	v_mul_f32_e32 v8, v200, v8
	v_mul_f32_e32 v9, v200, v9
	v_mul_f32_e32 v10, v200, v10
	v_mul_f32_e32 v11, v200, v11
	v_mul_f32_e32 v12, v200, v12
	v_mul_f32_e32 v13, v200, v13
	v_mul_f32_e32 v14, v200, v14
	v_mul_f32_e32 v15, v200, v15
	v_exp_f32_e32 v8, v8
	v_exp_f32_e32 v9, v9
	v_exp_f32_e32 v10, v10
	v_exp_f32_e32 v11, v11
	v_exp_f32_e32 v12, v12
	v_exp_f32_e32 v13, v13
	v_exp_f32_e32 v14, v14
	v_exp_f32_e32 v15, v15
	v_fma_f32 v8, v8, v201, v201
	v_fma_f32 v9, v9, v201, v201
	v_fma_f32 v10, v10, v201, v201
	v_fma_f32 v11, v11, v201, v201
	v_fma_f32 v12, v12, v201, v201
	v_fma_f32 v13, v13, v201, v201
	v_fma_f32 v14, v14, v201, v201
	v_fma_f32 v15, v15, v201, v201
	v_rcp_f32_e32 v8, v8
	v_rcp_f32_e32 v9, v9
	v_rcp_f32_e32 v10, v10
	v_rcp_f32_e32 v11, v11
	v_rcp_f32_e32 v12, v12
	v_rcp_f32_e32 v13, v13
	v_rcp_f32_e32 v14, v14
	v_rcp_f32_e32 v15, v15
	v_pk_mul_f32 v[0:1], v[0:1], v[8:9]
	v_pk_mul_f32 v[2:3], v[2:3], v[10:11]
	v_pk_mul_f32 v[4:5], v[4:5], v[12:13]
	v_pk_mul_f32 v[6:7], v[6:7], v[14:15]
	v_cvt_pk_bf16_f32 v8, v4, v5
	v_cvt_pk_bf16_f32 v9, v6, v7
	v_cvt_pk_bf16_f32 v10, v0, v1
	v_cvt_pk_bf16_f32 v11, v2, v3
	global_store_dwordx4 v[166:167], v[8:11], off nt
	s_cbranch_vccnz .LBB0_668
	s_andn2_b64 vcc, exec, s[6:7]
	s_cbranch_vccnz .LBB0_667
	s_barrier
	s_branch .LBB0_667

; __device__ __forceinline__ unsigned cvt_pk_bf16(float lo, float hi) { const cvt_f32x2_t v = {lo, hi}; const cvt_bf16x2_t b = __builtin_convertvector(v, cvt_bf16x2_t); return __builtin_bit_cast(unsigned, b); }
; __device__ __forceinline__ float rstd_from_slots(const float* slots, int row, int fq) {
;     const f32x4 s4 = *(const f32x4*)(slots + (size_t)row * 16 + 4 * fq);
;     float s = (s4[0] + s4[1]) + (s4[2] + s4[3]);
;     s += __shfl_xor(s, 16); s += __shfl_xor(s, 32);
;     return __builtin_amdgcn_rsqf(s * (1.0f / 1024.0f) + RMS_EPS_F);
; __device__ __forceinline__ float silu_mul(float g, float u) { return g * u * __builtin_amdgcn_rcpf(1.0f + __builtin_amdgcn_exp2f(g * -1.4426950408889634f)); }
;     __device__ __forceinline__ void operator()(const f32x4 (&acc)[2][2][4][2], const Unit& u, int wr, int wc, int fr, int fq) const {
;         const int row0 = u.pm * BM + wr * 64 + fr; const int col0 = u.pn * HALF + wc * 32 + 8 * fq;
; #pragma unroll
;         for (int ai = 0; ai < 2; ++ai)
; #pragma unroll
;             for (int m = 0; m < 4; ++m) { const int row = row0 + ai * HALF + m * 16;
;                 const float sc = rstd_from_slots(slots, row, fq);
;                 const f32x4 g0 = acc[ai][0][m][0] * sc, g1 = acc[ai][0][m][1] * sc, u0 = acc[ai][1][m][0] * sc, u1 = acc[ai][1][m][1] * sc;
;                 u32x4 w; w.x = cvt_pk_bf16(silu_mul(g0[0], u0[0]), silu_mul(g0[1], u0[1])); w.y = cvt_pk_bf16(silu_mul(g0[2], u0[2]), silu_mul(g0[3], u0[3]));
;                 w.z = cvt_pk_bf16(silu_mul(g1[0], u1[0]), silu_mul(g1[1], u1[1])); w.w = cvt_pk_bf16(silu_mul(g1[2], u1[2]), silu_mul(g1[3], u1[3]));
;                 __builtin_nontemporal_store(w, (u32x4*)(O + (size_t)row * ldc + col0)); }
.LBB0_1114:
	v_xor_b32_e32 v216, 16, v160
	v_xor_b32_e32 v217, 32, v160
	v_lshlrev_b32_e32 v216, 2, v216
	v_lshlrev_b32_e32 v217, 2, v217
	s_waitcnt vmcnt(0)
	v_add_f32_e32 v172, v172, v173
	v_add_f32_e32 v173, v175, v174
	v_add_f32_e32 v176, v176, v177
	v_add_f32_e32 v177, v179, v178
	v_add_f32_e32 v180, v180, v181
	v_add_f32_e32 v181, v183, v182
	v_add_f32_e32 v184, v184, v185
	v_add_f32_e32 v185, v187, v186
	v_add_f32_e32 v188, v188, v189
	v_add_f32_e32 v189, v191, v190
	v_add_f32_e32 v192, v192, v193
	v_add_f32_e32 v193, v195, v194
	v_add_f32_e32 v196, v196, v197
	v_add_f32_e32 v197, v199, v198
	v_add_f32_e32 v200, v200, v201
	v_add_f32_e32 v201, v203, v202
	v_add_f32_e32 v172, v172, v173
	v_add_f32_e32 v176, v176, v177
	v_add_f32_e32 v180, v180, v181
	v_add_f32_e32 v184, v184, v185
	v_add_f32_e32 v188, v188, v189
	v_add_f32_e32 v192, v192, v193
	v_add_f32_e32 v196, v196, v197
	v_add_f32_e32 v200, v200, v201
	ds_bpermute_b32 v173, v216, v172
	ds_bpermute_b32 v177, v216, v176
	ds_bpermute_b32 v181, v216, v180
	ds_bpermute_b32 v185, v216, v184
	ds_bpermute_b32 v189, v216, v188
	ds_bpermute_b32 v193, v216, v192
	ds_bpermute_b32 v197, v216, v196
	ds_bpermute_b32 v201, v216, v200
	s_waitcnt lgkmcnt(0)
	v_add_f32_e32 v172, v172, v173
	v_add_f32_e32 v176, v176, v177
	v_add_f32_e32 v180, v180, v181
	v_add_f32_e32 v184, v184, v185
	v_add_f32_e32 v188, v188, v189
	v_add_f32_e32 v192, v192, v193
	v_add_f32_e32 v196, v196, v197
	v_add_f32_e32 v200, v200, v201
	ds_bpermute_b32 v173, v217, v172
	ds_bpermute_b32 v177, v217, v176
	ds_bpermute_b32 v181, v217, v180
	ds_bpermute_b32 v185, v217, v184
	ds_bpermute_b32 v189, v217, v188
	ds_bpermute_b32 v193, v217, v192
	ds_bpermute_b32 v197, v217, v196
	ds_bpermute_b32 v201, v217, v200
	s_waitcnt lgkmcnt(0)
	v_add_f32_e32 v172, v172, v173
	v_add_f32_e32 v176, v176, v177
	v_add_f32_e32 v180, v180, v181
	v_add_f32_e32 v184, v184, v185
	v_add_f32_e32 v188, v188, v189
	v_add_f32_e32 v192, v192, v193
	v_add_f32_e32 v196, v196, v197
	v_add_f32_e32 v200, v200, v201
	v_fmamk_f32 v173, v172, 0x3a800000, v161
	v_fmamk_f32 v177, v176, 0x3a800000, v161
	v_fmamk_f32 v181, v180, 0x3a800000, v161
	v_fmamk_f32 v185, v184, 0x3a800000, v161
	v_fmamk_f32 v189, v188, 0x3a800000, v161
	v_fmamk_f32 v193, v192, 0x3a800000, v161
	v_fmamk_f32 v197, v196, 0x3a800000, v161
	v_fmamk_f32 v201, v200, 0x3a800000, v161
	v_rsq_f32_e32 v172, v173
	v_rsq_f32_e32 v176, v177
	v_rsq_f32_e32 v180, v181
	v_rsq_f32_e32 v184, v185
	v_rsq_f32_e32 v188, v189
	v_rsq_f32_e32 v192, v193
	v_rsq_f32_e32 v196, v197
	v_rsq_f32_e32 v200, v201
	v_mul_f32_e32 v172, 0xbfb8aa3b, v172
	v_mul_f32_e32 v176, 0xbfb8aa3b, v176
	v_mul_f32_e32 v180, 0xbfb8aa3b, v180
	v_mul_f32_e32 v184, 0xbfb8aa3b, v184
	v_mul_f32_e32 v188, 0xbfb8aa3b, v188
	v_mul_f32_e32 v192, 0xbfb8aa3b, v192
	v_mul_f32_e32 v196, 0xbfb8aa3b, v196
	v_mul_f32_e32 v200, 0xbfb8aa3b, v200
	v_lshl_add_u32 v150, s0, 8, v152
	v_lshl_or_b32 v148, s1, 7, v156
	v_mov_b64_e32 v[146:147], s[10:11]
	v_ashrrev_i32_e32 v149, 31, v148
	v_lshlrev_b64 v[148:149], 1, v[148:149]
	s_andn2_b64 vcc, exec, s[2:3]
	v_mad_i64_i32 v[164:165], s[0:1], v150, s56, v[146:147]
	v_lshl_add_u64 v[164:165], v[164:165], 0, v[148:149]
	s_mov_b64 s[0:1], -1
	s_mov_b32 s98, 0x16000
	s_mov_b32 s99, 0
	v_pk_mul_f32 v[112:113], v[120:121], v[112:113]
	v_pk_mul_f32 v[114:115], v[122:123], v[114:115]
	v_pk_mul_f32 v[116:117], v[124:125], v[116:117]
	v_pk_mul_f32 v[118:119], v[126:127], v[118:119]
	v_mul_f32_e32 v120, v172, v120
	v_mul_f32_e32 v121, v172, v121
	v_mul_f32_e32 v122, v172, v122
	v_mul_f32_e32 v123, v172, v123
	v_mul_f32_e32 v124, v172, v124
	v_mul_f32_e32 v125, v172, v125
	v_mul_f32_e32 v126, v172, v126
	v_mul_f32_e32 v127, v172, v127
	v_exp_f32_e32 v120, v120
	v_exp_f32_e32 v121, v121
	v_exp_f32_e32 v122, v122
	v_exp_f32_e32 v123, v123
	v_exp_f32_e32 v124, v124
	v_exp_f32_e32 v125, v125
	v_exp_f32_e32 v126, v126
	v_exp_f32_e32 v127, v127
	v_fma_f32 v120, v120, v173, v173
	v_fma_f32 v121, v121, v173, v173
	v_fma_f32 v122, v122, v173, v173
	v_fma_f32 v123, v123, v173, v173
	v_fma_f32 v124, v124, v173, v173
	v_fma_f32 v125, v125, v173, v173
	v_fma_f32 v126, v126, v173, v173
	v_fma_f32 v127, v127, v173, v173
	v_rcp_f32_e32 v120, v120
	v_rcp_f32_e32 v121, v121
	v_rcp_f32_e32 v122, v122
	v_rcp_f32_e32 v123, v123
	v_rcp_f32_e32 v124, v124
	v_rcp_f32_e32 v125, v125
	v_rcp_f32_e32 v126, v126
	v_rcp_f32_e32 v127, v127
	v_pk_mul_f32 v[112:113], v[112:113], v[120:121]
	v_pk_mul_f32 v[114:115], v[114:115], v[122:123]
	v_pk_mul_f32 v[116:117], v[116:117], v[124:125]
	v_pk_mul_f32 v[118:119], v[118:119], v[126:127]
	v_cvt_pk_bf16_f32 v120, v116, v117
	v_cvt_pk_bf16_f32 v121, v118, v119
	v_cvt_pk_bf16_f32 v122, v112, v113
	v_cvt_pk_bf16_f32 v123, v114, v115
	global_store_dwordx4 v[164:165], v[120:123], off nt
	v_lshl_add_u64 v[166:167], v[164:165], 0, s[98:99]
	v_pk_mul_f32 v[96:97], v[104:105], v[96:97]
	v_pk_mul_f32 v[98:99], v[106:107], v[98:99]
	v_pk_mul_f32 v[100:101], v[108:109], v[100:101]
	v_pk_mul_f32 v[102:103], v[110:111], v[102:103]
	v_mul_f32_e32 v104, v176, v104
	v_mul_f32_e32 v105, v176, v105
	v_mul_f32_e32 v106, v176, v106
	v_mul_f32_e32 v107, v176, v107
	v_mul_f32_e32 v108, v176, v108
	v_mul_f32_e32 v109, v176, v109
	v_mul_f32_e32 v110, v176, v110
	v_mul_f32_e32 v111, v176, v111
	v_exp_f32_e32 v104, v104
	v_exp_f32_e32 v105, v105
	v_exp_f32_e32 v106, v106
	v_exp_f32_e32 v107, v107
	v_exp_f32_e32 v108, v108
	v_exp_f32_e32 v109, v109
	v_exp_f32_e32 v110, v110
	v_exp_f32_e32 v111, v111
	v_fma_f32 v104, v104, v177, v177
	v_fma_f32 v105, v105, v177, v177
	v_fma_f32 v106, v106, v177, v177
	v_fma_f32 v107, v107, v177, v177
; __device__ __forceinline__ unsigned cvt_pk_bf16(float lo, float hi) { const cvt_f32x2_t v = {lo, hi}; const cvt_bf16x2_t b = __builtin_convertvector(v, cvt_bf16x2_t); return __builtin_bit_cast(unsigned, b); }
; __device__ __forceinline__ float silu_mul(float g, float u) { return g * u * __builtin_amdgcn_rcpf(1.0f + __builtin_amdgcn_exp2f(g * -1.4426950408889634f)); }
;     __device__ __forceinline__ void operator()(const f32x4 (&acc)[2][2][4][2], const Unit& u, int wr, int wc, int fr, int fq) const {
;     ...
; #pragma unroll
;         for (int ai = 0; ai < 2; ++ai)
; #pragma unroll
;             for (int m = 0; m < 4; ++m) { const int row = row0 + ai * HALF + m * 16;
;                 const float sc = rstd_from_slots(slots, row, fq);
;                 const f32x4 g0 = acc[ai][0][m][0] * sc, g1 = acc[ai][0][m][1] * sc, u0 = acc[ai][1][m][0] * sc, u1 = acc[ai][1][m][1] * sc;
;                 u32x4 w; w.x = cvt_pk_bf16(silu_mul(g0[0], u0[0]), silu_mul(g0[1], u0[1])); w.y = cvt_pk_bf16(silu_mul(g0[2], u0[2]), silu_mul(g0[3], u0[3]));
;                 w.z = cvt_pk_bf16(silu_mul(g1[0], u1[0]), silu_mul(g1[1], u1[1])); w.w = cvt_pk_bf16(silu_mul(g1[2], u1[2]), silu_mul(g1[3], u1[3]));
;                 __builtin_nontemporal_store(w, (u32x4*)(O + (size_t)row * ldc + col0)); }
	v_fma_f32 v108, v108, v177, v177
	v_fma_f32 v109, v109, v177, v177
	v_fma_f32 v110, v110, v177, v177
	v_fma_f32 v111, v111, v177, v177
	v_rcp_f32_e32 v104, v104
	v_rcp_f32_e32 v105, v105
	v_rcp_f32_e32 v106, v106
	v_rcp_f32_e32 v107, v107
	v_rcp_f32_e32 v108, v108
	v_rcp_f32_e32 v109, v109
	v_rcp_f32_e32 v110, v110
	v_rcp_f32_e32 v111, v111
	v_pk_mul_f32 v[96:97], v[96:97], v[104:105]
	v_pk_mul_f32 v[98:99], v[98:99], v[106:107]
	v_pk_mul_f32 v[100:101], v[100:101], v[108:109]
	v_pk_mul_f32 v[102:103], v[102:103], v[110:111]
	v_cvt_pk_bf16_f32 v104, v100, v101
	v_cvt_pk_bf16_f32 v105, v102, v103
	v_cvt_pk_bf16_f32 v106, v96, v97
	v_cvt_pk_bf16_f32 v107, v98, v99
	global_store_dwordx4 v[166:167], v[104:107], off nt
	v_lshl_add_u64 v[164:165], v[166:167], 0, s[98:99]
	v_pk_mul_f32 v[80:81], v[88:89], v[80:81]
	v_pk_mul_f32 v[82:83], v[90:91], v[82:83]
	v_pk_mul_f32 v[84:85], v[92:93], v[84:85]
	v_pk_mul_f32 v[86:87], v[94:95], v[86:87]
	v_mul_f32_e32 v88, v180, v88
	v_mul_f32_e32 v89, v180, v89
	v_mul_f32_e32 v90, v180, v90
	v_mul_f32_e32 v91, v180, v91
	v_mul_f32_e32 v92, v180, v92
	v_mul_f32_e32 v93, v180, v93
	v_mul_f32_e32 v94, v180, v94
	v_mul_f32_e32 v95, v180, v95
	v_exp_f32_e32 v88, v88
	v_exp_f32_e32 v89, v89
	v_exp_f32_e32 v90, v90
	v_exp_f32_e32 v91, v91
	v_exp_f32_e32 v92, v92
	v_exp_f32_e32 v93, v93
	v_exp_f32_e32 v94, v94
	v_exp_f32_e32 v95, v95
	v_fma_f32 v88, v88, v181, v181
	v_fma_f32 v89, v89, v181, v181
	v_fma_f32 v90, v90, v181, v181
	v_fma_f32 v91, v91, v181, v181
	v_fma_f32 v92, v92, v181, v181
	v_fma_f32 v93, v93, v181, v181
	v_fma_f32 v94, v94, v181, v181
	v_fma_f32 v95, v95, v181, v181
	v_rcp_f32_e32 v88, v88
	v_rcp_f32_e32 v89, v89
	v_rcp_f32_e32 v90, v90
	v_rcp_f32_e32 v91, v91
	v_rcp_f32_e32 v92, v92
	v_rcp_f32_e32 v93, v93
	v_rcp_f32_e32 v94, v94
	v_rcp_f32_e32 v95, v95
	v_pk_mul_f32 v[80:81], v[80:81], v[88:89]
	v_pk_mul_f32 v[82:83], v[82:83], v[90:91]
	v_pk_mul_f32 v[84:85], v[84:85], v[92:93]
	v_pk_mul_f32 v[86:87], v[86:87], v[94:95]
	v_cvt_pk_bf16_f32 v88, v84, v85
	v_cvt_pk_bf16_f32 v89, v86, v87
	v_cvt_pk_bf16_f32 v90, v80, v81
	v_cvt_pk_bf16_f32 v91, v82, v83
	global_store_dwordx4 v[164:165], v[88:91], off nt
	v_lshl_add_u64 v[166:167], v[164:165], 0, s[98:99]
	v_pk_mul_f32 v[64:65], v[72:73], v[64:65]
	v_pk_mul_f32 v[66:67], v[74:75], v[66:67]
	v_pk_mul_f32 v[68:69], v[76:77], v[68:69]
	v_pk_mul_f32 v[70:71], v[78:79], v[70:71]
	v_mul_f32_e32 v72, v184, v72
	v_mul_f32_e32 v73, v184, v73
	v_mul_f32_e32 v74, v184, v74
	v_mul_f32_e32 v75, v184, v75
	v_mul_f32_e32 v76, v184, v76
	v_mul_f32_e32 v77, v184, v77
	v_mul_f32_e32 v78, v184, v78
	v_mul_f32_e32 v79, v184, v79
	v_exp_f32_e32 v72, v72
	v_exp_f32_e32 v73, v73
	v_exp_f32_e32 v74, v74
	v_exp_f32_e32 v75, v75
	v_exp_f32_e32 v76, v76
	v_exp_f32_e32 v77, v77
	v_exp_f32_e32 v78, v78
	v_exp_f32_e32 v79, v79
	v_fma_f32 v72, v72, v185, v185
	v_fma_f32 v73, v73, v185, v185
	v_fma_f32 v74, v74, v185, v185
	v_fma_f32 v75, v75, v185, v185
	v_fma_f32 v76, v76, v185, v185
	v_fma_f32 v77, v77, v185, v185
	v_fma_f32 v78, v78, v185, v185
	v_fma_f32 v79, v79, v185, v185
	v_rcp_f32_e32 v72, v72
	v_rcp_f32_e32 v73, v73
	v_rcp_f32_e32 v74, v74
	v_rcp_f32_e32 v75, v75
	v_rcp_f32_e32 v76, v76
	v_rcp_f32_e32 v77, v77
	v_rcp_f32_e32 v78, v78
	v_rcp_f32_e32 v79, v79
	v_pk_mul_f32 v[64:65], v[64:65], v[72:73]
	v_pk_mul_f32 v[66:67], v[66:67], v[74:75]
	v_pk_mul_f32 v[68:69], v[68:69], v[76:77]
	v_pk_mul_f32 v[70:71], v[70:71], v[78:79]
	v_cvt_pk_bf16_f32 v72, v68, v69
	v_cvt_pk_bf16_f32 v73, v70, v71
	v_cvt_pk_bf16_f32 v74, v64, v65
	v_cvt_pk_bf16_f32 v75, v66, v67
	global_store_dwordx4 v[166:167], v[72:75], off nt
	s_mov_b32 s98, 0x6e000
	v_lshl_add_u64 v[164:165], v[166:167], 0, s[98:99]
	s_mov_b32 s98, 0x16000
	v_pk_mul_f32 v[48:49], v[56:57], v[48:49]
	v_pk_mul_f32 v[50:51], v[58:59], v[50:51]
	v_pk_mul_f32 v[52:53], v[60:61], v[52:53]
	v_pk_mul_f32 v[54:55], v[62:63], v[54:55]
	v_mul_f32_e32 v56, v188, v56
	v_mul_f32_e32 v57, v188, v57
	v_mul_f32_e32 v58, v188, v58
	v_mul_f32_e32 v59, v188, v59
	v_mul_f32_e32 v60, v188, v60
	v_mul_f32_e32 v61, v188, v61
	v_mul_f32_e32 v62, v188, v62
	v_mul_f32_e32 v63, v188, v63
	v_exp_f32_e32 v56, v56
	v_exp_f32_e32 v57, v57
	v_exp_f32_e32 v58, v58
	v_exp_f32_e32 v59, v59
	v_exp_f32_e32 v60, v60
	v_exp_f32_e32 v61, v61
	v_exp_f32_e32 v62, v62
	v_exp_f32_e32 v63, v63
	v_fma_f32 v56, v56, v189, v189
	v_fma_f32 v57, v57, v189, v189
	v_fma_f32 v58, v58, v189, v189
	v_fma_f32 v59, v59, v189, v189
	v_fma_f32 v60, v60, v189, v189
	v_fma_f32 v61, v61, v189, v189
	v_fma_f32 v62, v62, v189, v189
	v_fma_f32 v63, v63, v189, v189
	v_rcp_f32_e32 v56, v56
	v_rcp_f32_e32 v57, v57
	v_rcp_f32_e32 v58, v58
	v_rcp_f32_e32 v59, v59
	v_rcp_f32_e32 v60, v60
	v_rcp_f32_e32 v61, v61
	v_rcp_f32_e32 v62, v62
	v_rcp_f32_e32 v63, v63
; __device__ __forceinline__ unsigned cvt_pk_bf16(float lo, float hi) { const cvt_f32x2_t v = {lo, hi}; const cvt_bf16x2_t b = __builtin_convertvector(v, cvt_bf16x2_t); return __builtin_bit_cast(unsigned, b); }
; __device__ __forceinline__ float silu_mul(float g, float u) { return g * u * __builtin_amdgcn_rcpf(1.0f + __builtin_amdgcn_exp2f(g * -1.4426950408889634f)); }
; #define PG8_BAR __builtin_amdgcn_s_barrier()
;     __device__ __forceinline__ void operator()(const f32x4 (&acc)[2][2][4][2], const Unit& u, int wr, int wc, int fr, int fq) const {
;     ...
; #pragma unroll
;         for (int ai = 0; ai < 2; ++ai)
; #pragma unroll
;             for (int m = 0; m < 4; ++m) { const int row = row0 + ai * HALF + m * 16;
;                 const float sc = rstd_from_slots(slots, row, fq);
;                 const f32x4 g0 = acc[ai][0][m][0] * sc, g1 = acc[ai][0][m][1] * sc, u0 = acc[ai][1][m][0] * sc, u1 = acc[ai][1][m][1] * sc;
;                 u32x4 w; w.x = cvt_pk_bf16(silu_mul(g0[0], u0[0]), silu_mul(g0[1], u0[1])); w.y = cvt_pk_bf16(silu_mul(g0[2], u0[2]), silu_mul(g0[3], u0[3]));
;                 w.z = cvt_pk_bf16(silu_mul(g1[0], u1[0]), silu_mul(g1[1], u1[1])); w.w = cvt_pk_bf16(silu_mul(g1[2], u1[2]), silu_mul(g1[3], u1[3]));
;                 __builtin_nontemporal_store(w, (u32x4*)(O + (size_t)row * ldc + col0)); }
; template <class Epi, class Sched, bool ALIGN_EPI = false, bool SP2 = false>
; __device__ __forceinline__ void gemm_phase(PG8_LAS unsigned char* lds, const Gemm g, const Sched& S, const Epi& E) {
;     ...
;         if constexpr (!Epi::AFTER_DRAIN) { E(acc, cur, wr, wc, fr, fq); S.done(cur); }
;         if (!has_next) break;
; #pragma unroll
;         for (int a = 0; a < 2; ++a)
; #pragma unroll
;             for (int b = 0; b < 2; ++b)
; #pragma unroll
;                 for (int m = 0; m < 4; ++m)
; #pragma unroll
;                     for (int n = 0; n < 2; ++n) acc[a][b][m][n] = (f32x4){0.f, 0.f, 0.f, 0.f};
;         cur = nxt; cA = nA; cB = nB; ++ui;
;         if constexpr (ALIGN_EPI) { if (wr == 1) PG8_BAR; }
	v_pk_mul_f32 v[48:49], v[48:49], v[56:57]
	v_pk_mul_f32 v[50:51], v[50:51], v[58:59]
	v_pk_mul_f32 v[52:53], v[52:53], v[60:61]
	v_pk_mul_f32 v[54:55], v[54:55], v[62:63]
	v_cvt_pk_bf16_f32 v56, v52, v53
	v_cvt_pk_bf16_f32 v57, v54, v55
	v_cvt_pk_bf16_f32 v58, v48, v49
	v_cvt_pk_bf16_f32 v59, v50, v51
	global_store_dwordx4 v[164:165], v[56:59], off nt
	v_lshl_add_u64 v[166:167], v[164:165], 0, s[98:99]
	v_pk_mul_f32 v[32:33], v[40:41], v[32:33]
	v_pk_mul_f32 v[34:35], v[42:43], v[34:35]
	v_pk_mul_f32 v[36:37], v[44:45], v[36:37]
	v_pk_mul_f32 v[38:39], v[46:47], v[38:39]
	v_mul_f32_e32 v40, v192, v40
	v_mul_f32_e32 v41, v192, v41
	v_mul_f32_e32 v42, v192, v42
	v_mul_f32_e32 v43, v192, v43
	v_mul_f32_e32 v44, v192, v44
	v_mul_f32_e32 v45, v192, v45
	v_mul_f32_e32 v46, v192, v46
	v_mul_f32_e32 v47, v192, v47
	v_exp_f32_e32 v40, v40
	v_exp_f32_e32 v41, v41
	v_exp_f32_e32 v42, v42
	v_exp_f32_e32 v43, v43
	v_exp_f32_e32 v44, v44
	v_exp_f32_e32 v45, v45
	v_exp_f32_e32 v46, v46
	v_exp_f32_e32 v47, v47
	v_fma_f32 v40, v40, v193, v193
	v_fma_f32 v41, v41, v193, v193
	v_fma_f32 v42, v42, v193, v193
	v_fma_f32 v43, v43, v193, v193
	v_fma_f32 v44, v44, v193, v193
	v_fma_f32 v45, v45, v193, v193
	v_fma_f32 v46, v46, v193, v193
	v_fma_f32 v47, v47, v193, v193
	v_rcp_f32_e32 v40, v40
	v_rcp_f32_e32 v41, v41
	v_rcp_f32_e32 v42, v42
	v_rcp_f32_e32 v43, v43
	v_rcp_f32_e32 v44, v44
	v_rcp_f32_e32 v45, v45
	v_rcp_f32_e32 v46, v46
	v_rcp_f32_e32 v47, v47
	v_pk_mul_f32 v[32:33], v[32:33], v[40:41]
	v_pk_mul_f32 v[34:35], v[34:35], v[42:43]
	v_pk_mul_f32 v[36:37], v[36:37], v[44:45]
	v_pk_mul_f32 v[38:39], v[38:39], v[46:47]
	v_cvt_pk_bf16_f32 v40, v36, v37
	v_cvt_pk_bf16_f32 v41, v38, v39
	v_cvt_pk_bf16_f32 v42, v32, v33
	v_cvt_pk_bf16_f32 v43, v34, v35
	global_store_dwordx4 v[166:167], v[40:43], off nt
	v_lshl_add_u64 v[164:165], v[166:167], 0, s[98:99]
	v_pk_mul_f32 v[16:17], v[24:25], v[16:17]
	v_pk_mul_f32 v[18:19], v[26:27], v[18:19]
	v_pk_mul_f32 v[20:21], v[28:29], v[20:21]
	v_pk_mul_f32 v[22:23], v[30:31], v[22:23]
	v_mul_f32_e32 v24, v196, v24
	v_mul_f32_e32 v25, v196, v25
	v_mul_f32_e32 v26, v196, v26
	v_mul_f32_e32 v27, v196, v27
	v_mul_f32_e32 v28, v196, v28
	v_mul_f32_e32 v29, v196, v29
	v_mul_f32_e32 v30, v196, v30
	v_mul_f32_e32 v31, v196, v31
	v_exp_f32_e32 v24, v24
	v_exp_f32_e32 v25, v25
	v_exp_f32_e32 v26, v26
	v_exp_f32_e32 v27, v27
	v_exp_f32_e32 v28, v28
	v_exp_f32_e32 v29, v29
	v_exp_f32_e32 v30, v30
	v_exp_f32_e32 v31, v31
	v_fma_f32 v24, v24, v197, v197
	v_fma_f32 v25, v25, v197, v197
	v_fma_f32 v26, v26, v197, v197
	v_fma_f32 v27, v27, v197, v197
	v_fma_f32 v28, v28, v197, v197
	v_fma_f32 v29, v29, v197, v197
	v_fma_f32 v30, v30, v197, v197
	v_fma_f32 v31, v31, v197, v197
	v_rcp_f32_e32 v24, v24
	v_rcp_f32_e32 v25, v25
	v_rcp_f32_e32 v26, v26
	v_rcp_f32_e32 v27, v27
	v_rcp_f32_e32 v28, v28
	v_rcp_f32_e32 v29, v29
	v_rcp_f32_e32 v30, v30
	v_rcp_f32_e32 v31, v31
	v_pk_mul_f32 v[16:17], v[16:17], v[24:25]
	v_pk_mul_f32 v[18:19], v[18:19], v[26:27]
	v_pk_mul_f32 v[20:21], v[20:21], v[28:29]
	v_pk_mul_f32 v[22:23], v[22:23], v[30:31]
	v_cvt_pk_bf16_f32 v24, v20, v21
	v_cvt_pk_bf16_f32 v25, v22, v23
	v_cvt_pk_bf16_f32 v26, v16, v17
	v_cvt_pk_bf16_f32 v27, v18, v19
	global_store_dwordx4 v[164:165], v[24:27], off nt
	v_lshl_add_u64 v[166:167], v[164:165], 0, s[98:99]
	v_pk_mul_f32 v[0:1], v[8:9], v[0:1]
	v_pk_mul_f32 v[2:3], v[10:11], v[2:3]
	v_pk_mul_f32 v[4:5], v[12:13], v[4:5]
	v_pk_mul_f32 v[6:7], v[14:15], v[6:7]
	v_mul_f32_e32 v8, v200, v8
	v_mul_f32_e32 v9, v200, v9
	v_mul_f32_e32 v10, v200, v10
	v_mul_f32_e32 v11, v200, v11
	v_mul_f32_e32 v12, v200, v12
	v_mul_f32_e32 v13, v200, v13
	v_mul_f32_e32 v14, v200, v14
	v_mul_f32_e32 v15, v200, v15
	v_exp_f32_e32 v8, v8
	v_exp_f32_e32 v9, v9
	v_exp_f32_e32 v10, v10
	v_exp_f32_e32 v11, v11
	v_exp_f32_e32 v12, v12
	v_exp_f32_e32 v13, v13
	v_exp_f32_e32 v14, v14
	v_exp_f32_e32 v15, v15
	v_fma_f32 v8, v8, v201, v201
	v_fma_f32 v9, v9, v201, v201
	v_fma_f32 v10, v10, v201, v201
	v_fma_f32 v11, v11, v201, v201
	v_fma_f32 v12, v12, v201, v201
	v_fma_f32 v13, v13, v201, v201
	v_fma_f32 v14, v14, v201, v201
	v_fma_f32 v15, v15, v201, v201
	v_rcp_f32_e32 v8, v8
	v_rcp_f32_e32 v9, v9
	v_rcp_f32_e32 v10, v10
	v_rcp_f32_e32 v11, v11
	v_rcp_f32_e32 v12, v12
	v_rcp_f32_e32 v13, v13
	v_rcp_f32_e32 v14, v14
	v_rcp_f32_e32 v15, v15
	v_pk_mul_f32 v[0:1], v[0:1], v[8:9]
	v_pk_mul_f32 v[2:3], v[2:3], v[10:11]
	v_pk_mul_f32 v[4:5], v[4:5], v[12:13]
	v_pk_mul_f32 v[6:7], v[6:7], v[14:15]
	v_cvt_pk_bf16_f32 v8, v4, v5
	v_cvt_pk_bf16_f32 v9, v6, v7
	v_cvt_pk_bf16_f32 v10, v0, v1
	v_cvt_pk_bf16_f32 v11, v2, v3
	global_store_dwordx4 v[166:167], v[8:11], off nt
	s_cbranch_vccnz .LBB0_1107
	s_andn2_b64 vcc, exec, s[6:7]
	s_cbranch_vccnz .LBB0_1106
	s_barrier
	s_branch .LBB0_1106
